# norm prompt-row loops: next row's 8 loads prefetched into spare registers before the current row's stores (one-row software pipeline)
# baseline (speedup 1.0000x reference)
; __device__ __forceinline__ const float* inp(const Params& p, int i) { asm volatile("" : "+s"(i)); return p.in[i]; }
; template <int MODE>
; __device__ __forceinline__ void norm_row(const Params& p, const f32x4 (&g)[8], int r, int lane, int nparts, float pscale) {
;     ...
;     const float* src = (MODE == 0) ? (r < 8192 ? inp(p, 0) + (size_t)r * 2048 : inp(p, 1) + (size_t)(r - 8192) * 2048) : X + (size_t)r * 2048;
;     f32x4 v[8]; float ss = 0.f;
; #pragma unroll
;     for (int i = 0; i < 8; ++i) v[i] = *(const f32x4*)(src + i * 256 + lane * 4);
;     if (MODE != 0 && nparts > 0 && r >= 8192) {
;         const float* pp = (const float*)(p.ws + WS_ST) + (size_t)(r - 8192) * 2048 + lane * 4;
;         f32x4 a[8];
; #pragma unroll
;         for (int i = 0; i < 8; ++i) a[i] = (f32x4){0.f, 0.f, 0.f, 0.f};
;         for (int k = 0; k < nparts; ++k) {
; #pragma unroll
;             for (int i = 0; i < 8; ++i) a[i] += *(const f32x4*)(pp + (size_t)k * (512 * 2048) + i * 256);
;         }
; #pragma unroll
;         for (int i = 0; i < 8; ++i) { v[i] += pscale * a[i]; *(f32x4*)(X + (size_t)r * 2048 + i * 256 + lane * 4) = v[i]; }
;     }
; #pragma unroll
;     for (int i = 0; i < 8; ++i) ss += v[i][0] * v[i][0] + v[i][1] * v[i][1] + v[i][2] * v[i][2] + v[i][3] * v[i][3];
; #pragma unroll
;     for (int o = 32; o >= 1; o >>= 1) ss += __shfl_xor(ss, o);
;     const float rstd = rsqrtf(ss * (1.f / 2048.f) + EPS);
; #pragma unroll
; template <int MODE>
; __device__ void phase_norm(const Params& p, const float* gamma, int nparts, float pscale) {
;     ...
;     for (int r = blockIdx.x * 8 + wave; r < 8192; r += gridDim.x * 8) norm_row<MODE>(p, g, r, lane, nparts, pscale);
.LBB0_36:
	s_or_b64 exec, exec, s[40:41]
	v_readlane_b32 s2, v252, 53
	s_nop 1
	v_add_u32_e32 v68, s2, v127
	s_movk_i32 s2, 0x2000
	v_cmp_gt_i32_e32 vcc, s2, v68
	s_and_saveexec_b64 s[40:41], vcc
	s_movk_i32 s18, 0x1fff
	s_cbranch_execz .LBB0_39
	v_cmp_lt_i32_e32 vcc, v165, v164
	v_readlane_b32 s4, v252, 51
	v_lshlrev_b32_e32 v132, 2, v126
	v_cndmask_b32_e32 v36, v161, v165, vcc
	v_cmp_lt_i32_e32 vcc, v166, v164
	v_lshlrev_b32_e32 v73, 2, v36
	v_readlane_b32 s5, v252, 52
	v_cndmask_b32_e32 v36, v161, v166, vcc
	v_cmp_lt_i32_e32 vcc, v167, v164
	v_lshlrev_b32_e32 v74, 2, v36
	v_readlane_b32 s2, v252, 36
	v_cndmask_b32_e32 v36, v161, v167, vcc
	v_cmp_lt_i32_e32 vcc, v168, v164
	v_lshlrev_b32_e32 v75, 2, v36
	v_bfe_u32 v79, v124, 3, 1
	v_cndmask_b32_e32 v36, v161, v168, vcc
	v_cmp_lt_i32_e32 vcc, v169, v164
	v_lshlrev_b32_e32 v76, 2, v36
	v_lshrrev_b32_e32 v81, 4, v125
	v_cndmask_b32_e32 v36, v161, v169, vcc
	v_cmp_lt_i32_e32 vcc, v170, v164
	v_lshlrev_b32_e32 v77, 2, v36
	v_lshl_add_u64 v[70:71], s[4:5], 0, v[132:133]
	v_cndmask_b32_e32 v36, v161, v170, vcc
	v_lshlrev_b32_e32 v78, 2, v36
	v_lshlrev_b32_e32 v36, 3, v125
	v_and_b32_e32 v80, 56, v36
	v_lshl_add_u32 v82, v127, 6, s2
	s_mov_b64 s[42:43], 0
	v_ashrrev_i32_e32 v69, 31, v68
	v_lshlrev_b64 v[232:233], 13, v[68:69]
	v_lshl_add_u64 v[232:233], v[70:71], 0, v[232:233]
	global_load_dwordx4 v[200:203], v[232:233], off
	global_load_dwordx4 v[204:207], v[232:233], off offset:1024
	global_load_dwordx4 v[208:211], v[232:233], off offset:2048
	global_load_dwordx4 v[212:215], v[232:233], off offset:3072
	v_add_co_u32_e32 v232, vcc, 0x1000, v232
	s_nop 1
	v_addc_co_u32_e32 v233, vcc, 0, v233, vcc
	global_load_dwordx4 v[216:219], v[232:233], off
	global_load_dwordx4 v[220:223], v[232:233], off offset:1024
	global_load_dwordx4 v[224:227], v[232:233], off offset:2048
	global_load_dwordx4 v[228:231], v[232:233], off offset:3072
	s_waitcnt vmcnt(0)
.LBB0_38:
	s_waitcnt vmcnt(8)
	v_mov_b64_e32 v[64:65], v[200:201]
	v_mov_b64_e32 v[66:67], v[202:203]
	v_mov_b64_e32 v[60:61], v[204:205]
	v_mov_b64_e32 v[62:63], v[206:207]
	v_mov_b64_e32 v[56:57], v[208:209]
	v_mov_b64_e32 v[58:59], v[210:211]
	v_mov_b64_e32 v[52:53], v[212:213]
	v_mov_b64_e32 v[54:55], v[214:215]
	v_mov_b64_e32 v[48:49], v[216:217]
	v_mov_b64_e32 v[50:51], v[218:219]
	v_mov_b64_e32 v[44:45], v[220:221]
	v_mov_b64_e32 v[46:47], v[222:223]
	v_mov_b64_e32 v[40:41], v[224:225]
	v_mov_b64_e32 v[42:43], v[226:227]
	v_mov_b64_e32 v[36:37], v[228:229]
	v_mov_b64_e32 v[38:39], v[230:231]
	v_and_b32_e32 v83, 0x2000, v82
	v_mul_f32_e32 v69, v65, v65
	v_mul_f32_e32 v72, v61, v61
	v_fmac_f32_e32 v69, v64, v64
	v_fmac_f32_e32 v72, v60, v60
	v_fmac_f32_e32 v69, v66, v66
	v_fmac_f32_e32 v72, v62, v62
	v_fmac_f32_e32 v69, v67, v67
	v_fmac_f32_e32 v72, v63, v63
	v_add_f32_e32 v69, v69, v72
	v_mul_f32_e32 v72, v57, v57
	v_fmac_f32_e32 v72, v56, v56
	v_fmac_f32_e32 v72, v58, v58
	v_fmac_f32_e32 v72, v59, v59
	v_add_f32_e32 v69, v69, v72
	v_mul_f32_e32 v72, v53, v53
	v_mov_b32_e32 v86, v49
	v_mov_b32_e32 v87, v45
	v_fmac_f32_e32 v72, v52, v52
	v_mov_b32_e32 v84, v48
	v_mov_b32_e32 v85, v44
	v_pk_mul_f32 v[86:87], v[86:87], v[86:87]
	v_fmac_f32_e32 v72, v54, v54
	v_pk_fma_f32 v[84:85], v[84:85], v[84:85], v[86:87]
	v_mov_b32_e32 v86, v50
	v_mov_b32_e32 v87, v46
	v_fmac_f32_e32 v72, v55, v55
	v_pk_fma_f32 v[84:85], v[86:87], v[86:87], v[84:85]
	v_mov_b32_e32 v86, v51
	v_mov_b32_e32 v87, v47
	v_add_f32_e32 v69, v69, v72
	v_pk_fma_f32 v[84:85], v[86:87], v[86:87], v[84:85]
	v_mov_b32_e32 v86, v41
	v_add_f32_e32 v69, v69, v84
	v_mov_b32_e32 v87, v37
	v_add_f32_e32 v69, v69, v85
	v_mov_b32_e32 v84, v40
	v_mov_b32_e32 v85, v36
	v_pk_mul_f32 v[86:87], v[86:87], v[86:87]
	s_nop 0
	v_pk_fma_f32 v[84:85], v[84:85], v[84:85], v[86:87]
	v_mov_b32_e32 v86, v42
	v_mov_b32_e32 v87, v38
	v_pk_fma_f32 v[84:85], v[86:87], v[86:87], v[84:85]
	v_mov_b32_e32 v86, v43
	v_mov_b32_e32 v87, v39
	v_pk_fma_f32 v[84:85], v[86:87], v[86:87], v[84:85]
	v_lshrrev_b32_e32 v86, 4, v82
	v_add_f32_e32 v69, v69, v84
	v_add_f32_e32 v69, v69, v85
	ds_bpermute_b32 v72, v73, v69
	v_lshrrev_b32_e32 v84, 3, v68
	v_and_or_b32 v84, v84, 14, v79
	v_and_or_b32 v85, v82, s15, v80
	v_lshlrev_b32_e32 v84, 10, v84
	s_waitcnt lgkmcnt(0)
	v_add_f32_e32 v69, v69, v72
	ds_bpermute_b32 v72, v74, v69
	v_and_b32_e32 v86, 32, v86
	v_bitop3_b32 v132, v85, v84, v86 bitop3:0xde
	v_lshlrev_b32_e32 v84, 1, v83
	v_mov_b32_e32 v85, v133
	s_waitcnt lgkmcnt(0)
	v_add_f32_e32 v69, v69, v72
	ds_bpermute_b32 v72, v75, v69
	v_lshl_add_u64 v[84:85], s[24:25], 0, v[84:85]
	v_lshl_add_u64 v[84:85], v[84:85], 0, v[132:133]
	v_add_u32_e32 v82, s38, v82
	s_waitcnt lgkmcnt(0)
	v_add_f32_e32 v69, v69, v72
	ds_bpermute_b32 v72, v76, v69
	s_waitcnt lgkmcnt(0)
	v_add_f32_e32 v69, v69, v72
	ds_bpermute_b32 v72, v77, v69
	s_waitcnt lgkmcnt(0)
	v_add_f32_e32 v69, v69, v72
	ds_bpermute_b32 v72, v78, v69
	s_waitcnt lgkmcnt(0)
; __device__ __forceinline__ unsigned cvt_pk_bf16(float lo, float hi) { f32x2 v = {lo, hi}; bf16x2v b = __builtin_convertvector(v, bf16x2v); return __builtin_bit_cast(unsigned, b); }
; template <int MODE>
; __device__ __forceinline__ void norm_row(const Params& p, const f32x4 (&g)[8], int r, int lane, int nparts, float pscale) {
;     ...
;     const float rstd = rsqrtf(ss * (1.f / 2048.f) + EPS);
; #pragma unroll
;     for (int i = 0; i < 8; ++i) {
;         if (MODE == 0) *(f32x4*)(X + (size_t)r * 2048 + i * 256 + lane * 4) = v[i];
;         const f32x4 o = v[i] * rstd * g[i];
;         if (MODE < 2) { u32x2 w; w.x = cvt_pk_bf16(o[0], o[1]); w.y = cvt_pk_bf16(o[2], o[3]); *(u32x2*)(H + pg8::img_off(r, i * 256 + lane * 4, 32)) = w; }
;         else *(f32x4*)(p.out + (size_t)r * 2048 + i * 256 + lane * 4) = o;
;     }
; template <int MODE>
; __device__ void phase_norm(const Params& p, const float* gamma, int nparts, float pscale) {
;     ...
;     for (int r = blockIdx.x * 8 + wave; r < 8192; r += gridDim.x * 8) norm_row<MODE>(p, g, r, lane, nparts, pscale);
	v_add_f32_e32 v69, v69, v72
	v_fmamk_f32 v69, v69, 0x3a000000, v134
	v_cmp_gt_f32_e32 vcc, s14, v69
	v_mul_f32_e32 v72, 0x4b800000, v69
	s_nop 0
	v_cndmask_b32_e32 v69, v69, v72, vcc
	v_rsq_f32_e32 v69, v69
	s_nop 0
	v_mul_f32_e32 v72, 0x45800000, v69
	v_cndmask_b32_e32 v72, v69, v72, vcc
	v_pk_mul_f32 v[64:65], v[64:65], v[72:73] op_sel_hi:[1,0]
	v_pk_mul_f32 v[66:67], v[66:67], v[72:73] op_sel_hi:[1,0]
	v_ashrrev_i32_e32 v69, 3, v68
	v_pk_mul_f32 v[66:67], v[6:7], v[66:67]
	v_pk_mul_f32 v[64:65], v[4:5], v[64:65]
	v_pk_mul_f32 v[60:61], v[60:61], v[72:73] op_sel_hi:[1,0]
	v_pk_mul_f32 v[62:63], v[62:63], v[72:73] op_sel_hi:[1,0]
	v_pk_mul_f32 v[56:57], v[56:57], v[72:73] op_sel_hi:[1,0]
	v_pk_mul_f32 v[58:59], v[58:59], v[72:73] op_sel_hi:[1,0]
	v_pk_mul_f32 v[52:53], v[52:53], v[72:73] op_sel_hi:[1,0]
	v_pk_mul_f32 v[54:55], v[54:55], v[72:73] op_sel_hi:[1,0]
	v_pk_mul_f32 v[48:49], v[48:49], v[72:73] op_sel_hi:[1,0]
	v_pk_mul_f32 v[50:51], v[50:51], v[72:73] op_sel_hi:[1,0]
	v_pk_mul_f32 v[44:45], v[44:45], v[72:73] op_sel_hi:[1,0]
	v_pk_mul_f32 v[46:47], v[46:47], v[72:73] op_sel_hi:[1,0]
	v_pk_mul_f32 v[40:41], v[40:41], v[72:73] op_sel_hi:[1,0]
	v_pk_mul_f32 v[42:43], v[42:43], v[72:73] op_sel_hi:[1,0]
	v_pk_mul_f32 v[36:37], v[36:37], v[72:73] op_sel_hi:[1,0]
	v_pk_mul_f32 v[38:39], v[38:39], v[72:73] op_sel_hi:[1,0]
	v_cvt_pk_bf16_f32 v64, v64, v65
	v_cvt_pk_bf16_f32 v65, v66, v67
	v_and_or_b32 v66, v69, s34, v81
	v_pk_mul_f32 v[62:63], v[10:11], v[62:63]
	v_pk_mul_f32 v[60:61], v[8:9], v[60:61]
	v_pk_mul_f32 v[58:59], v[14:15], v[58:59]
	v_pk_mul_f32 v[56:57], v[12:13], v[56:57]
	v_pk_mul_f32 v[54:55], v[18:19], v[54:55]
	v_pk_mul_f32 v[52:53], v[16:17], v[52:53]
	v_pk_mul_f32 v[50:51], v[22:23], v[50:51]
	v_pk_mul_f32 v[48:49], v[20:21], v[48:49]
	v_pk_mul_f32 v[46:47], v[26:27], v[46:47]
	v_pk_mul_f32 v[44:45], v[24:25], v[44:45]
	v_pk_mul_f32 v[42:43], v[30:31], v[42:43]
	v_pk_mul_f32 v[40:41], v[28:29], v[40:41]
	v_pk_mul_f32 v[38:39], v[34:35], v[38:39]
	v_pk_mul_f32 v[36:37], v[32:33], v[36:37]
	v_cvt_pk_bf16_f32 v60, v60, v61
	v_cvt_pk_bf16_f32 v61, v62, v63
	v_or_b32_e32 v62, 4, v66
	v_cvt_pk_bf16_f32 v56, v56, v57
	v_cvt_pk_bf16_f32 v57, v58, v59
	v_or_b32_e32 v58, 8, v66
	v_cvt_pk_bf16_f32 v52, v52, v53
	v_cvt_pk_bf16_f32 v53, v54, v55
	v_or_b32_e32 v54, 12, v66
	v_cvt_pk_bf16_f32 v48, v48, v49
	v_cvt_pk_bf16_f32 v49, v50, v51
	v_or_b32_e32 v50, 16, v66
	v_cvt_pk_bf16_f32 v44, v44, v45
	v_cvt_pk_bf16_f32 v45, v46, v47
	v_or_b32_e32 v46, 20, v66
	v_cvt_pk_bf16_f32 v40, v40, v41
	v_cvt_pk_bf16_f32 v41, v42, v43
	v_or_b32_e32 v42, 24, v66
	v_cvt_pk_bf16_f32 v36, v36, v37
	v_cvt_pk_bf16_f32 v37, v38, v39
	v_or_b32_e32 v38, 28, v66
	v_ashrrev_i32_e32 v67, 31, v66
	v_ashrrev_i32_e32 v63, 31, v62
	v_ashrrev_i32_e32 v59, 31, v58
	v_ashrrev_i32_e32 v55, 31, v54
	v_ashrrev_i32_e32 v51, 31, v50
	v_ashrrev_i32_e32 v47, 31, v46
	v_ashrrev_i32_e32 v43, 31, v42
	v_ashrrev_i32_e32 v39, 31, v38
	v_add_u32_e32 v68, s27, v68
	v_lshlrev_b64 v[86:87], 15, v[66:67]
	v_lshlrev_b64 v[62:63], 15, v[62:63]
	v_lshlrev_b64 v[58:59], 15, v[58:59]
	v_lshlrev_b64 v[54:55], 15, v[54:55]
	v_lshlrev_b64 v[50:51], 15, v[50:51]
	v_lshlrev_b64 v[46:47], 15, v[46:47]
	v_lshlrev_b64 v[42:43], 15, v[42:43]
	v_lshlrev_b64 v[38:39], 15, v[38:39]
	v_cmp_lt_i32_e32 vcc, s18, v68
	v_lshl_add_u64 v[86:87], v[84:85], 0, v[86:87]
	v_lshl_add_u64 v[62:63], v[84:85], 0, v[62:63]
	v_lshl_add_u64 v[58:59], v[84:85], 0, v[58:59]
	v_lshl_add_u64 v[54:55], v[84:85], 0, v[54:55]
	v_lshl_add_u64 v[50:51], v[84:85], 0, v[50:51]
	v_lshl_add_u64 v[46:47], v[84:85], 0, v[46:47]
	v_lshl_add_u64 v[42:43], v[84:85], 0, v[42:43]
	v_lshl_add_u64 v[38:39], v[84:85], 0, v[38:39]
	s_or_b64 s[42:43], vcc, s[42:43]
	v_ashrrev_i32_e32 v69, 31, v68
	v_lshlrev_b64 v[232:233], 13, v[68:69]
	v_lshl_add_u64 v[232:233], v[70:71], 0, v[232:233]
	global_load_dwordx4 v[200:203], v[232:233], off
	global_load_dwordx4 v[204:207], v[232:233], off offset:1024
	global_load_dwordx4 v[208:211], v[232:233], off offset:2048
	global_load_dwordx4 v[212:215], v[232:233], off offset:3072
	v_add_co_u32_e32 v232, vcc, 0x1000, v232
	s_nop 1
	v_addc_co_u32_e32 v233, vcc, 0, v233, vcc
	global_load_dwordx4 v[216:219], v[232:233], off
	global_load_dwordx4 v[220:223], v[232:233], off offset:1024
	global_load_dwordx4 v[224:227], v[232:233], off offset:2048
	global_load_dwordx4 v[228:231], v[232:233], off offset:3072
	global_store_dwordx2 v[86:87], v[64:65], off
	global_store_dwordx2 v[62:63], v[60:61], off
	global_store_dwordx2 v[58:59], v[56:57], off
	global_store_dwordx2 v[54:55], v[52:53], off
	global_store_dwordx2 v[50:51], v[48:49], off
	global_store_dwordx2 v[46:47], v[44:45], off
	global_store_dwordx2 v[42:43], v[40:41], off
	global_store_dwordx2 v[38:39], v[36:37], off
	s_andn2_b64 exec, exec, s[42:43]
	s_cbranch_execnz .LBB0_38
.LBB0_39:
	s_or_b64 exec, exec, s[40:41]
	s_waitcnt vmcnt(0)
	s_mov_b64 s[4:5], 0

; __device__ __forceinline__ const float* inp(const Params& p, int i) { asm volatile("" : "+s"(i)); return p.in[i]; }
; template <int MODE>
; __device__ __forceinline__ void norm_row(const Params& p, const f32x4 (&g)[8], int r, int lane, int nparts, float pscale) {
;     ...
;     const float* src = (MODE == 0) ? (r < 8192 ? inp(p, 0) + (size_t)r * 2048 : inp(p, 1) + (size_t)(r - 8192) * 2048) : X + (size_t)r * 2048;
;     f32x4 v[8]; float ss = 0.f;
; #pragma unroll
;     for (int i = 0; i < 8; ++i) v[i] = *(const f32x4*)(src + i * 256 + lane * 4);
;     if (MODE != 0 && nparts > 0 && r >= 8192) {
;         const float* pp = (const float*)(p.ws + WS_ST) + (size_t)(r - 8192) * 2048 + lane * 4;
;         f32x4 a[8];
; #pragma unroll
;         for (int i = 0; i < 8; ++i) a[i] = (f32x4){0.f, 0.f, 0.f, 0.f};
;         for (int k = 0; k < nparts; ++k) {
; #pragma unroll
;             for (int i = 0; i < 8; ++i) a[i] += *(const f32x4*)(pp + (size_t)k * (512 * 2048) + i * 256);
;         }
; #pragma unroll
;         for (int i = 0; i < 8; ++i) { v[i] += pscale * a[i]; *(f32x4*)(X + (size_t)r * 2048 + i * 256 + lane * 4) = v[i]; }
;     }
; #pragma unroll
;     for (int i = 0; i < 8; ++i) ss += v[i][0] * v[i][0] + v[i][1] * v[i][1] + v[i][2] * v[i][2] + v[i][3] * v[i][3];
; #pragma unroll
;     for (int o = 32; o >= 1; o >>= 1) ss += __shfl_xor(ss, o);
;     const float rstd = rsqrtf(ss * (1.f / 2048.f) + EPS);
; #pragma unroll
; template <int MODE>
; __device__ void phase_norm(const Params& p, const float* gamma, int nparts, float pscale) {
;     ...
;     for (int r = blockIdx.x * 8 + wave; r < 8192; r += gridDim.x * 8) norm_row<MODE>(p, g, r, lane, nparts, pscale);
.LBB0_725:
	s_or_b64 exec, exec, s[12:13]
	v_readlane_b32 s2, v252, 53
	s_nop 1
	v_add_u32_e32 v68, s2, v178
	s_movk_i32 s2, 0x2000
	v_cmp_gt_i32_e32 vcc, s2, v68
	s_and_saveexec_b64 s[12:13], vcc
	s_movk_i32 s18, 0x1fff
	s_cbranch_execz .LBB0_728
	v_cmp_lt_i32_e32 vcc, v165, v164
	v_readlane_b32 s4, v252, 51
	v_lshlrev_b32_e32 v132, 2, v177
	v_cndmask_b32_e32 v36, v161, v165, vcc
	v_cmp_lt_i32_e32 vcc, v166, v164
	v_lshlrev_b32_e32 v73, 2, v36
	v_readlane_b32 s5, v252, 52
	v_cndmask_b32_e32 v36, v161, v166, vcc
	v_cmp_lt_i32_e32 vcc, v167, v164
	v_lshlrev_b32_e32 v74, 2, v36
	v_readlane_b32 s2, v252, 36
	v_cndmask_b32_e32 v36, v161, v167, vcc
	v_cmp_lt_i32_e32 vcc, v168, v164
	v_lshlrev_b32_e32 v75, 2, v36
	v_bfe_u32 v79, v137, 3, 1
	v_cndmask_b32_e32 v36, v161, v168, vcc
	v_cmp_lt_i32_e32 vcc, v169, v164
	v_lshlrev_b32_e32 v76, 2, v36
	v_lshrrev_b32_e32 v81, 4, v176
	v_cndmask_b32_e32 v36, v161, v169, vcc
	v_cmp_lt_i32_e32 vcc, v170, v164
	v_lshlrev_b32_e32 v77, 2, v36
	v_lshl_add_u64 v[70:71], s[4:5], 0, v[132:133]
	v_cndmask_b32_e32 v36, v161, v170, vcc
	v_lshlrev_b32_e32 v78, 2, v36
	v_lshlrev_b32_e32 v36, 3, v176
	v_and_b32_e32 v80, 56, v36
	v_lshl_add_u32 v82, v178, 6, s2
	s_mov_b64 s[40:41], 0
	v_ashrrev_i32_e32 v69, 31, v68
	v_lshlrev_b64 v[232:233], 13, v[68:69]
	v_lshl_add_u64 v[232:233], v[70:71], 0, v[232:233]
	global_load_dwordx4 v[200:203], v[232:233], off
	global_load_dwordx4 v[204:207], v[232:233], off offset:1024
	global_load_dwordx4 v[208:211], v[232:233], off offset:2048
	global_load_dwordx4 v[212:215], v[232:233], off offset:3072
	v_add_co_u32_e32 v232, vcc, 0x1000, v232
	s_nop 1
	v_addc_co_u32_e32 v233, vcc, 0, v233, vcc
	global_load_dwordx4 v[216:219], v[232:233], off
	global_load_dwordx4 v[220:223], v[232:233], off offset:1024
	global_load_dwordx4 v[224:227], v[232:233], off offset:2048
	global_load_dwordx4 v[228:231], v[232:233], off offset:3072
	s_waitcnt vmcnt(0)
.LBB0_727:
	s_waitcnt vmcnt(8)
	v_mov_b64_e32 v[64:65], v[200:201]
	v_mov_b64_e32 v[66:67], v[202:203]
	v_mov_b64_e32 v[60:61], v[204:205]
	v_mov_b64_e32 v[62:63], v[206:207]
	v_mov_b64_e32 v[56:57], v[208:209]
	v_mov_b64_e32 v[58:59], v[210:211]
	v_mov_b64_e32 v[52:53], v[212:213]
	v_mov_b64_e32 v[54:55], v[214:215]
	v_mov_b64_e32 v[48:49], v[216:217]
	v_mov_b64_e32 v[50:51], v[218:219]
	v_mov_b64_e32 v[44:45], v[220:221]
	v_mov_b64_e32 v[46:47], v[222:223]
	v_mov_b64_e32 v[40:41], v[224:225]
	v_mov_b64_e32 v[42:43], v[226:227]
	v_mov_b64_e32 v[36:37], v[228:229]
	v_mov_b64_e32 v[38:39], v[230:231]
	v_and_b32_e32 v83, 0x2000, v82
	v_mul_f32_e32 v69, v65, v65
	v_mul_f32_e32 v72, v61, v61
	v_fmac_f32_e32 v69, v64, v64
	v_fmac_f32_e32 v72, v60, v60
	v_fmac_f32_e32 v69, v66, v66
	v_fmac_f32_e32 v72, v62, v62
	v_fmac_f32_e32 v69, v67, v67
	v_fmac_f32_e32 v72, v63, v63
	v_add_f32_e32 v69, v69, v72
	v_mul_f32_e32 v72, v57, v57
	v_fmac_f32_e32 v72, v56, v56
	v_fmac_f32_e32 v72, v58, v58
	v_fmac_f32_e32 v72, v59, v59
	v_add_f32_e32 v69, v69, v72
	v_mul_f32_e32 v72, v53, v53
	v_mov_b32_e32 v86, v49
	v_mov_b32_e32 v87, v45
	v_fmac_f32_e32 v72, v52, v52
	v_mov_b32_e32 v84, v48
	v_mov_b32_e32 v85, v44
	v_pk_mul_f32 v[86:87], v[86:87], v[86:87]
	v_fmac_f32_e32 v72, v54, v54
	v_pk_fma_f32 v[84:85], v[84:85], v[84:85], v[86:87]
	v_mov_b32_e32 v86, v50
	v_mov_b32_e32 v87, v46
	v_fmac_f32_e32 v72, v55, v55
	v_pk_fma_f32 v[84:85], v[86:87], v[86:87], v[84:85]
	v_mov_b32_e32 v86, v51
	v_mov_b32_e32 v87, v47
	v_add_f32_e32 v69, v69, v72
	v_pk_fma_f32 v[84:85], v[86:87], v[86:87], v[84:85]
	v_mov_b32_e32 v86, v41
	v_add_f32_e32 v69, v69, v84
	v_mov_b32_e32 v87, v37
	v_add_f32_e32 v69, v69, v85
	v_mov_b32_e32 v84, v40
	v_mov_b32_e32 v85, v36
	v_pk_mul_f32 v[86:87], v[86:87], v[86:87]
	s_nop 0
	v_pk_fma_f32 v[84:85], v[84:85], v[84:85], v[86:87]
	v_mov_b32_e32 v86, v42
	v_mov_b32_e32 v87, v38
	v_pk_fma_f32 v[84:85], v[86:87], v[86:87], v[84:85]
	v_mov_b32_e32 v86, v43
	v_mov_b32_e32 v87, v39
	v_pk_fma_f32 v[84:85], v[86:87], v[86:87], v[84:85]
	v_lshrrev_b32_e32 v86, 4, v82
	v_add_f32_e32 v69, v69, v84
	v_add_f32_e32 v69, v69, v85
	ds_bpermute_b32 v72, v73, v69
	v_lshrrev_b32_e32 v84, 3, v68
	v_and_or_b32 v84, v84, 14, v79
	v_and_or_b32 v85, v82, s15, v80
	v_lshlrev_b32_e32 v84, 10, v84
	s_waitcnt lgkmcnt(0)
	v_add_f32_e32 v69, v69, v72
	ds_bpermute_b32 v72, v74, v69
	v_and_b32_e32 v86, 32, v86
	v_bitop3_b32 v132, v85, v84, v86 bitop3:0xde
	v_lshlrev_b32_e32 v84, 1, v83
	v_mov_b32_e32 v85, v133
	s_waitcnt lgkmcnt(0)
	v_add_f32_e32 v69, v69, v72
	ds_bpermute_b32 v72, v75, v69
	v_lshl_add_u64 v[84:85], s[24:25], 0, v[84:85]
	v_lshl_add_u64 v[84:85], v[84:85], 0, v[132:133]
	v_add_u32_e32 v82, s38, v82
	s_waitcnt lgkmcnt(0)
	v_add_f32_e32 v69, v69, v72
	ds_bpermute_b32 v72, v76, v69
	s_waitcnt lgkmcnt(0)
	v_add_f32_e32 v69, v69, v72
	ds_bpermute_b32 v72, v77, v69
	s_waitcnt lgkmcnt(0)
	v_add_f32_e32 v69, v69, v72
	ds_bpermute_b32 v72, v78, v69
	s_waitcnt lgkmcnt(0)
; __device__ __forceinline__ unsigned cvt_pk_bf16(float lo, float hi) { f32x2 v = {lo, hi}; bf16x2v b = __builtin_convertvector(v, bf16x2v); return __builtin_bit_cast(unsigned, b); }
; template <int MODE>
; __device__ __forceinline__ void norm_row(const Params& p, const f32x4 (&g)[8], int r, int lane, int nparts, float pscale) {
;     ...
;     const float rstd = rsqrtf(ss * (1.f / 2048.f) + EPS);
; #pragma unroll
;     for (int i = 0; i < 8; ++i) {
;         if (MODE == 0) *(f32x4*)(X + (size_t)r * 2048 + i * 256 + lane * 4) = v[i];
;         const f32x4 o = v[i] * rstd * g[i];
;         if (MODE < 2) { u32x2 w; w.x = cvt_pk_bf16(o[0], o[1]); w.y = cvt_pk_bf16(o[2], o[3]); *(u32x2*)(H + pg8::img_off(r, i * 256 + lane * 4, 32)) = w; }
;         else *(f32x4*)(p.out + (size_t)r * 2048 + i * 256 + lane * 4) = o;
;     }
; template <int MODE>
; __device__ void phase_norm(const Params& p, const float* gamma, int nparts, float pscale) {
;     ...
;     for (int r = blockIdx.x * 8 + wave; r < 8192; r += gridDim.x * 8) norm_row<MODE>(p, g, r, lane, nparts, pscale);
	v_add_f32_e32 v69, v69, v72
	v_fmamk_f32 v69, v69, 0x3a000000, v134
	v_cmp_gt_f32_e32 vcc, s14, v69
	v_mul_f32_e32 v72, 0x4b800000, v69
	s_nop 0
	v_cndmask_b32_e32 v69, v69, v72, vcc
	v_rsq_f32_e32 v69, v69
	s_nop 0
	v_mul_f32_e32 v72, 0x45800000, v69
	v_cndmask_b32_e32 v72, v69, v72, vcc
	v_pk_mul_f32 v[64:65], v[64:65], v[72:73] op_sel_hi:[1,0]
	v_pk_mul_f32 v[66:67], v[66:67], v[72:73] op_sel_hi:[1,0]
	v_ashrrev_i32_e32 v69, 3, v68
	v_pk_mul_f32 v[66:67], v[6:7], v[66:67]
	v_pk_mul_f32 v[64:65], v[4:5], v[64:65]
	v_pk_mul_f32 v[60:61], v[60:61], v[72:73] op_sel_hi:[1,0]
	v_pk_mul_f32 v[62:63], v[62:63], v[72:73] op_sel_hi:[1,0]
	v_pk_mul_f32 v[56:57], v[56:57], v[72:73] op_sel_hi:[1,0]
	v_pk_mul_f32 v[58:59], v[58:59], v[72:73] op_sel_hi:[1,0]
	v_pk_mul_f32 v[52:53], v[52:53], v[72:73] op_sel_hi:[1,0]
	v_pk_mul_f32 v[54:55], v[54:55], v[72:73] op_sel_hi:[1,0]
	v_pk_mul_f32 v[48:49], v[48:49], v[72:73] op_sel_hi:[1,0]
	v_pk_mul_f32 v[50:51], v[50:51], v[72:73] op_sel_hi:[1,0]
	v_pk_mul_f32 v[44:45], v[44:45], v[72:73] op_sel_hi:[1,0]
	v_pk_mul_f32 v[46:47], v[46:47], v[72:73] op_sel_hi:[1,0]
	v_pk_mul_f32 v[40:41], v[40:41], v[72:73] op_sel_hi:[1,0]
	v_pk_mul_f32 v[42:43], v[42:43], v[72:73] op_sel_hi:[1,0]
	v_pk_mul_f32 v[36:37], v[36:37], v[72:73] op_sel_hi:[1,0]
	v_pk_mul_f32 v[38:39], v[38:39], v[72:73] op_sel_hi:[1,0]
	v_cvt_pk_bf16_f32 v64, v64, v65
	v_cvt_pk_bf16_f32 v65, v66, v67
	v_and_or_b32 v66, v69, s34, v81
	v_pk_mul_f32 v[62:63], v[10:11], v[62:63]
	v_pk_mul_f32 v[60:61], v[8:9], v[60:61]
	v_pk_mul_f32 v[58:59], v[14:15], v[58:59]
	v_pk_mul_f32 v[56:57], v[12:13], v[56:57]
	v_pk_mul_f32 v[54:55], v[18:19], v[54:55]
	v_pk_mul_f32 v[52:53], v[16:17], v[52:53]
	v_pk_mul_f32 v[50:51], v[22:23], v[50:51]
	v_pk_mul_f32 v[48:49], v[20:21], v[48:49]
	v_pk_mul_f32 v[46:47], v[26:27], v[46:47]
	v_pk_mul_f32 v[44:45], v[24:25], v[44:45]
	v_pk_mul_f32 v[42:43], v[30:31], v[42:43]
	v_pk_mul_f32 v[40:41], v[28:29], v[40:41]
	v_pk_mul_f32 v[38:39], v[34:35], v[38:39]
	v_pk_mul_f32 v[36:37], v[32:33], v[36:37]
	v_cvt_pk_bf16_f32 v60, v60, v61
	v_cvt_pk_bf16_f32 v61, v62, v63
	v_or_b32_e32 v62, 4, v66
	v_cvt_pk_bf16_f32 v56, v56, v57
	v_cvt_pk_bf16_f32 v57, v58, v59
	v_or_b32_e32 v58, 8, v66
	v_cvt_pk_bf16_f32 v52, v52, v53
	v_cvt_pk_bf16_f32 v53, v54, v55
	v_or_b32_e32 v54, 12, v66
	v_cvt_pk_bf16_f32 v48, v48, v49
	v_cvt_pk_bf16_f32 v49, v50, v51
	v_or_b32_e32 v50, 16, v66
	v_cvt_pk_bf16_f32 v44, v44, v45
	v_cvt_pk_bf16_f32 v45, v46, v47
	v_or_b32_e32 v46, 20, v66
	v_cvt_pk_bf16_f32 v40, v40, v41
	v_cvt_pk_bf16_f32 v41, v42, v43
	v_or_b32_e32 v42, 24, v66
	v_cvt_pk_bf16_f32 v36, v36, v37
	v_cvt_pk_bf16_f32 v37, v38, v39
	v_or_b32_e32 v38, 28, v66
	v_ashrrev_i32_e32 v67, 31, v66
	v_ashrrev_i32_e32 v63, 31, v62
	v_ashrrev_i32_e32 v59, 31, v58
	v_ashrrev_i32_e32 v55, 31, v54
	v_ashrrev_i32_e32 v51, 31, v50
	v_ashrrev_i32_e32 v47, 31, v46
	v_ashrrev_i32_e32 v43, 31, v42
	v_ashrrev_i32_e32 v39, 31, v38
	v_add_u32_e32 v68, s27, v68
	v_lshlrev_b64 v[86:87], 15, v[66:67]
	v_lshlrev_b64 v[62:63], 15, v[62:63]
	v_lshlrev_b64 v[58:59], 15, v[58:59]
	v_lshlrev_b64 v[54:55], 15, v[54:55]
	v_lshlrev_b64 v[50:51], 15, v[50:51]
	v_lshlrev_b64 v[46:47], 15, v[46:47]
	v_lshlrev_b64 v[42:43], 15, v[42:43]
	v_lshlrev_b64 v[38:39], 15, v[38:39]
	v_cmp_lt_i32_e32 vcc, s18, v68
	v_lshl_add_u64 v[86:87], v[84:85], 0, v[86:87]
	v_lshl_add_u64 v[62:63], v[84:85], 0, v[62:63]
	v_lshl_add_u64 v[58:59], v[84:85], 0, v[58:59]
	v_lshl_add_u64 v[54:55], v[84:85], 0, v[54:55]
	v_lshl_add_u64 v[50:51], v[84:85], 0, v[50:51]
	v_lshl_add_u64 v[46:47], v[84:85], 0, v[46:47]
	v_lshl_add_u64 v[42:43], v[84:85], 0, v[42:43]
	v_lshl_add_u64 v[38:39], v[84:85], 0, v[38:39]
	s_or_b64 s[40:41], vcc, s[40:41]
	v_ashrrev_i32_e32 v69, 31, v68
	v_lshlrev_b64 v[232:233], 13, v[68:69]
	v_lshl_add_u64 v[232:233], v[70:71], 0, v[232:233]
	global_load_dwordx4 v[200:203], v[232:233], off
	global_load_dwordx4 v[204:207], v[232:233], off offset:1024
	global_load_dwordx4 v[208:211], v[232:233], off offset:2048
	global_load_dwordx4 v[212:215], v[232:233], off offset:3072
	v_add_co_u32_e32 v232, vcc, 0x1000, v232
	s_nop 1
	v_addc_co_u32_e32 v233, vcc, 0, v233, vcc
	global_load_dwordx4 v[216:219], v[232:233], off
	global_load_dwordx4 v[220:223], v[232:233], off offset:1024
	global_load_dwordx4 v[224:227], v[232:233], off offset:2048
	global_load_dwordx4 v[228:231], v[232:233], off offset:3072
	global_store_dwordx2 v[86:87], v[64:65], off
	global_store_dwordx2 v[62:63], v[60:61], off
	global_store_dwordx2 v[58:59], v[56:57], off
	global_store_dwordx2 v[54:55], v[52:53], off
	global_store_dwordx2 v[50:51], v[48:49], off
	global_store_dwordx2 v[46:47], v[44:45], off
	global_store_dwordx2 v[42:43], v[40:41], off
	global_store_dwordx2 v[38:39], v[36:37], off
	s_andn2_b64 exec, exec, s[40:41]
	s_cbranch_execnz .LBB0_727
.LBB0_728:
	s_or_b64 exec, exec, s[12:13]
	s_waitcnt vmcnt(0)
	s_mov_b64 s[4:5], 0

; __device__ __forceinline__ const float* inp(const Params& p, int i) { asm volatile("" : "+s"(i)); return p.in[i]; }
; template <int MODE>
; __device__ __forceinline__ void norm_row(const Params& p, const f32x4 (&g)[8], int r, int lane, int nparts, float pscale) {
;     ...
;     const float* src = (MODE == 0) ? (r < 8192 ? inp(p, 0) + (size_t)r * 2048 : inp(p, 1) + (size_t)(r - 8192) * 2048) : X + (size_t)r * 2048;
;     f32x4 v[8]; float ss = 0.f;
; #pragma unroll
;     for (int i = 0; i < 8; ++i) v[i] = *(const f32x4*)(src + i * 256 + lane * 4);
; template <int MODE>
; __device__ void phase_norm(const Params& p, const float* gamma, int nparts, float pscale) {
;     ...
;     if (wave < 2) for (int s = blockIdx.x * 2 + wave; s < 512; s += gridDim.x * 2) norm_row<MODE>(p, g, 8192 + s, lane, nparts, pscale);
;     for (int r = blockIdx.x * 8 + wave; r < 8192; r += gridDim.x * 8) norm_row<MODE>(p, g, r, lane, nparts, pscale);
.LBB0_754:
	s_or_b64 exec, exec, s[12:13]
	v_readlane_b32 s2, v252, 53
	s_nop 1
	v_add_u32_e32 v68, s2, v178
	s_movk_i32 s2, 0x2000
	v_cmp_gt_i32_e32 vcc, s2, v68
	s_and_saveexec_b64 s[12:13], vcc
	s_movk_i32 s18, 0x1fff
	s_cbranch_execz .LBB0_757
	v_cmp_lt_i32_e32 vcc, v165, v164
	v_readlane_b32 s4, v252, 51
	v_lshlrev_b32_e32 v132, 2, v176
	v_cndmask_b32_e32 v36, v161, v165, vcc
	v_cmp_lt_i32_e32 vcc, v166, v164
	v_lshlrev_b32_e32 v73, 2, v36
	v_readlane_b32 s5, v252, 52
	v_cndmask_b32_e32 v36, v161, v166, vcc
	v_cmp_lt_i32_e32 vcc, v167, v164
	v_lshlrev_b32_e32 v74, 2, v36
	v_readlane_b32 s2, v252, 36
	v_cndmask_b32_e32 v36, v161, v167, vcc
	v_cmp_lt_i32_e32 vcc, v168, v164
	v_lshlrev_b32_e32 v75, 2, v36
	v_bfe_u32 v79, v177, 3, 1
	v_cndmask_b32_e32 v36, v161, v168, vcc
	v_cmp_lt_i32_e32 vcc, v169, v164
	v_lshlrev_b32_e32 v76, 2, v36
	v_lshrrev_b32_e32 v81, 4, v137
	v_cndmask_b32_e32 v36, v161, v169, vcc
	v_cmp_lt_i32_e32 vcc, v170, v164
	v_lshlrev_b32_e32 v77, 2, v36
	v_lshl_add_u64 v[70:71], s[4:5], 0, v[132:133]
	v_cndmask_b32_e32 v36, v161, v170, vcc
	v_lshlrev_b32_e32 v78, 2, v36
	v_lshlrev_b32_e32 v36, 3, v137
	v_and_b32_e32 v80, 56, v36
	v_lshl_add_u32 v82, v178, 6, s2
	s_mov_b64 s[40:41], 0
	v_ashrrev_i32_e32 v69, 31, v68
	v_lshlrev_b64 v[232:233], 13, v[68:69]
	v_lshl_add_u64 v[232:233], v[70:71], 0, v[232:233]
	global_load_dwordx4 v[200:203], v[232:233], off
	global_load_dwordx4 v[204:207], v[232:233], off offset:1024
	global_load_dwordx4 v[208:211], v[232:233], off offset:2048
	global_load_dwordx4 v[212:215], v[232:233], off offset:3072
	v_add_co_u32_e32 v232, vcc, 0x1000, v232
	s_nop 1
	v_addc_co_u32_e32 v233, vcc, 0, v233, vcc
	global_load_dwordx4 v[216:219], v[232:233], off
	global_load_dwordx4 v[220:223], v[232:233], off offset:1024
	global_load_dwordx4 v[224:227], v[232:233], off offset:2048
	global_load_dwordx4 v[228:231], v[232:233], off offset:3072
	s_waitcnt vmcnt(0)

; template <int MODE>
; __device__ void phase_norm(const Params& p, const float* gamma, int nparts, float pscale) {
;     ...
;     for (int r = blockIdx.x * 8 + wave; r < 8192; r += gridDim.x * 8) norm_row<MODE>(p, g, r, lane, nparts, pscale);
; }
.LBB0_757:
	s_or_b64 exec, exec, s[12:13]
	s_waitcnt vmcnt(0)
